# code placement: 56 bytes of never-executed padding in front of the first differential-attention tile loop (complement behind it), nothing else changed vs v5
# baseline (speedup 1.0000x reference)
; __device__ __forceinline__ int lane_id() { int l; asm volatile("v_mbcnt_lo_u32_b32 %0, -1, 0\n\tv_mbcnt_hi_u32_b32 %0, -1, %0" : "=v"(l)); return l; }
; #define LOADK(dst, t) do { _Pragma("unroll") for (int j = 0; j < NKC; ++j) if (j == 0 || k1) dst[j] = *(const u32x4*)(kh + (size_t)(((t) + rot) & (NT - 1)) * 64 * DQK + (size_t)(tid + 512 * j) * 8); } while (0)
; #define LOADV(dst, t) do { _Pragma("unroll") for (int j = 0; j < NVC; ++j) dst[j] = *(const u32x4*)(vg0 + (size_t)(64 * j) * S + (size_t)(((t) + rot) & (NT - 1)) * 64); } while (0)
; #pragma unroll
;   for (int sl = 0; sl < 8; ++sl) m = max(m, kmx[sl * 64 + idx]);
;   return sqrtf(__uint_as_float(m)); }
; template <int DQK, int DV>
; __device__ __forceinline__ void attn_pass(const bf16_t* __restrict__ qh, const bf16_t* __restrict__ kh, const bf16_t* __restrict__ vth, int q0, char* smem, f32x16 (&o)[DV / 32], float kmax, int wvp) {
;   constexpr int KP = (DQK + 8) * 2, VP = 144, KSB = 64 * KP, VSB = DV * VP;
;   constexpr int CK = DQK / 8, TKC = 64 * CK, NKC = (TKC + 511) / 512, NVC = DV / 64, NKS = DQK / 16, NEB = DV / 32, NT = S / 64;
;   char* sK = smem; char* sV = smem + 2 * KSB;
;   int tid = wvp * 64 + lane_id(); asm volatile("" : "+v"(tid));
;   const int lane = tid & 63, wid = tid >> 6, r = lane & 31, h = lane >> 5;
;   bf16x8 qf[NKS];
;   {
;     const bf16_t* qrow = qh + (size_t)(q0 + 32 * wid + r) * DQK + 8 * h;
; #pragma unroll
;     for (int ks = 0; ks < NKS; ++ks) qf[ks] = *(const bf16x8*)(qrow + 16 * ks);
;   }
;   int klo[NKC], vlo[NVC];
;   const bf16_t* vg0 = vth + (size_t)(tid >> 3) * S + (tid & 7) * 8;
;   const bool k1 = (TKC % 512 == 0) || (tid < TKC % 512);
; #pragma unroll
;   for (int j = 0; j < NKC; ++j) { const int c = tid + 512 * j; klo[j] = (c / CK) * KP + (c % CK) * 16; }
; #pragma unroll
;   for (int j = 0; j < NVC; ++j) { const int c = tid + 512 * j; vlo[j] = (c >> 3) * VP + (c & 7) * 16; }
;   u32x4 rk[NKC], rv[NVC], rk1[NKC];
;   const int rot = (int)((blockIdx.x >> 3) * 4u) & (NT - 1);
;     ...
;   LOADK(rk, 0); LOADV(rv, 0); LOADK(rk1, 1);
.LBB0_575:
	s_lshl_b32 s4, s36, 21
	s_bfe_u32 s50, s36, 0x10002
	s_and_b32 s45, s36, 3
	s_and_b32 s4, s4, 0xe00000
	s_add_u32 s12, s48, s4
	s_addc_u32 s13, s49, 0
	s_lshl_b32 s4, s36, 5
	s_and_b32 s37, s4, 0xffffff00
	s_lshl_b32 s4, s50, 3
	s_lshl_b32 s5, s45, 1
	s_or_b32 s44, s4, s5
	s_lshl_b32 s6, s44, 20
	s_add_u32 s4, s86, s6
	s_addc_u32 s5, s87, 0
	s_add_u32 s6, s88, s6
	s_addc_u32 s7, s89, 0
	s_lshl_b32 s8, s44, 2
	v_mov_b32_e32 v0, s8
	global_load_dword v12, v0, s[46:47]
	global_load_dword v13, v0, s[46:47] offset:256
	global_load_dword v14, v0, s[46:47] offset:512
	global_load_dword v15, v0, s[46:47] offset:768
	global_load_dword v18, v0, s[46:47] offset:1024
	global_load_dword v19, v0, s[46:47] offset:1280
	global_load_dword v20, v0, s[46:47] offset:1536
	global_load_dword v21, v0, s[46:47] offset:1792
	v_mbcnt_lo_u32_b32 v0, -1, 0
	v_mbcnt_hi_u32_b32 v0, -1, v0
	s_mov_b32 s51, s2
	v_add_u32_e32 v0, s27, v0
	s_mov_b32 s52, s1
	v_and_b32_e32 v32, 31, v0
	v_ashrrev_i32_e32 v1, 1, v0
	v_and_b32_e32 v1, 0xffffffe0, v1
	v_or_b32_e32 v2, s37, v32
	v_add_u32_e32 v2, v2, v1
	v_ashrrev_i32_e32 v3, 31, v2
	v_lshlrev_b64 v[2:3], 7, v[2:3]
	v_lshrrev_b32_e32 v28, 1, v0
	v_lshl_add_u64 v[2:3], s[4:5], 0, v[2:3]
	v_and_b32_e32 v208, 16, v28
	v_lshl_add_u64 v[4:5], v[2:3], 0, v[208:209]
	global_load_dwordx4 v[176:179], v[4:5], off
	global_load_dwordx4 v[180:183], v[4:5], off offset:32
	global_load_dwordx4 v[184:187], v[4:5], off offset:64
	global_load_dwordx4 v[188:191], v[4:5], off offset:96
	v_ashrrev_i32_e32 v6, 3, v0
	v_ashrrev_i32_e32 v1, 31, v0
	v_lshlrev_b32_e32 v2, 4, v0
	v_add_u32_e32 v3, 0x200, v0
	v_ashrrev_i32_e32 v7, 31, v6
	s_add_u32 s4, s6, s21
	v_lshrrev_b32_e32 v9, 29, v1
	v_and_b32_e32 v8, 0x70, v2
	v_lshrrev_b32_e32 v16, 3, v3
	v_lshlrev_b64 v[10:11], 14, v[6:7]
	s_addc_u32 s5, s7, 0
	v_lshlrev_b64 v[2:3], 4, v[0:1]
	v_add_u32_e32 v1, v0, v9
	v_mad_u64_u32 v[210:211], s[16:17], v6, s20, v[8:9]
	v_mad_u64_u32 v[212:213], s[16:17], v16, s20, v[8:9]
	v_mov_b32_e32 v9, v209
	v_lshl_add_u64 v[6:7], s[12:13], 0, v[10:11]
	v_lshl_add_u64 v[22:23], s[4:5], 0, v[2:3]
	v_lshl_add_u64 v[214:215], v[6:7], 0, v[8:9]
	v_add_co_u32_e32 v16, vcc, s23, v22
	v_lshl_add_u64 v[24:25], v[214:215], 0, s[10:11]
	s_nop 0
	v_addc_co_u32_e32 v17, vcc, 0, v23, vcc
	v_add_co_u32_e64 v26, s[4:5], s22, v24
	global_load_dwordx4 v[4:7], v[22:23], off
	global_load_dwordx4 v[8:11], v[24:25], off
	v_addc_co_u32_e64 v27, s[4:5], 0, v25, s[4:5]
	v_lshrrev_b32_e32 v29, 3, v1
	v_and_b32_e32 v1, 0xffffff8, v1
	v_sub_u32_e32 v1, v0, v1
	v_mul_lo_u32 v29, v29, s20
	v_lshl_add_u32 v211, v1, 4, v29
	v_and_b32_e32 v1, 19, v0
	v_lshlrev_b32_e32 v0, 1, v0
	v_and_b32_e32 v0, 8, v0
	v_lshl_add_u64 v[216:217], s[6:7], 0, v[2:3]
	v_mov_b32_e32 v218, 0
	s_mov_b32 s53, s9
	v_mov_b32_e32 v2, v209
	v_mov_b32_e32 v3, v209
	v_mov_b32_e32 v40, v209
	v_mov_b32_e32 v41, v209
	v_mov_b32_e32 v42, v209
	v_mov_b32_e32 v43, v209
	v_mov_b32_e32 v44, v209
	v_mov_b32_e32 v45, v209
	v_mov_b32_e32 v46, v209
	v_mov_b32_e32 v47, v209
	v_mov_b32_e32 v48, 0
	v_mov_b32_e32 v49, v209
	s_waitcnt vmcnt(12)
	v_max_u32_e32 v12, v12, v13
	v_mov_b32_e32 v50, v209
	s_waitcnt vmcnt(10)
	v_max3_u32 v12, v12, v14, v15
	v_mov_b32_e32 v51, v209
	s_waitcnt vmcnt(8)
	v_max3_u32 v12, v12, v18, v19
	v_mov_b32_e32 v52, v209
	s_waitcnt vmcnt(6)
	v_max3_u32 v12, v12, v20, v21
	v_mul_f32_e32 v13, 0x4f800000, v12
	v_cmp_gt_f32_e32 vcc, s3, v12
	v_mov_b32_e32 v53, v209
	v_mov_b32_e32 v54, v209
	v_cndmask_b32_e32 v30, v12, v13, vcc
	global_load_dwordx4 v[12:15], v[26:27], off
	global_load_dwordx4 v[18:21], v[16:17], off
	v_sqrt_f32_e32 v31, v30
	s_barrier
; __device__ __forceinline__ int swz23(int r) { return (r & ~12) | ((r & 4) << 1) | ((r & 8) >> 1); }
; #define LOADK(dst, t) do { _Pragma("unroll") for (int j = 0; j < NKC; ++j) if (j == 0 || k1) dst[j] = *(const u32x4*)(kh + (size_t)(((t) + rot) & (NT - 1)) * 64 * DQK + (size_t)(tid + 512 * j) * 8); } while (0)
; #define LOADV(dst, t) do { _Pragma("unroll") for (int j = 0; j < NVC; ++j) dst[j] = *(const u32x4*)(vg0 + (size_t)(64 * j) * S + (size_t)(((t) + rot) & (NT - 1)) * 64); } while (0)
; #define STOREK(src, slot) do { _Pragma("unroll") for (int j = 0; j < NKC; ++j) if (j == 0 || k1) *(u32x4*)(sK + (slot) * KSB + klo[j]) = src[j]; } while (0)
; #define STOREV(src, slot) do { _Pragma("unroll") for (int j = 0; j < NVC; ++j) *(u32x4*)(sV + (slot) * VSB + vlo[j]) = src[j]; } while (0)
; template <int DQK, int DV>
; __device__ __forceinline__ void attn_pass(const bf16_t* __restrict__ qh, const bf16_t* __restrict__ kh, const bf16_t* __restrict__ vth, int q0, char* smem, f32x16 (&o)[DV / 32], float kmax, int wvp) {
;     ...
;   float l_run = 0.f;
;   f32x16 negm;
;   {
;     float qq = 0.f;
; #pragma unroll
;     for (int ks = 0; ks < NKS; ++ks)
; #pragma unroll
;       for (int j = 0; j < 8; ++j) { const float t = bf2f((unsigned short)qf[ks][j]); qq += t * t; }
;     { auto rr = __builtin_amdgcn_permlane32_swap(__float_as_uint(qq), __float_as_uint(qq), false, false); qq = __uint_as_float(rr[0]) + __uint_as_float(rr[1]); }
;     const float mref = sqrtf(qq) * kmax * 1.01f + 0.01f;
; #pragma unroll
;     for (int i = 0; i < 16; ++i) negm[i] = -mref;
;   }
;   __syncthreads();
;   STOREK(rk, 0); STOREV(rv, 0); STOREK(rk1, 1);
;   LOADK(rk, 2); LOADV(rv, 1);
;   const int kofs = swz23(r) * KP + 16 * h, vofs = r * VP + 16 * h;
;   __syncthreads();
;   f32x16 sA, sB;
;     ...
;   f32x16 sA0, sA1, sB0, sB1;
;   QKT(sA, 0);
	v_add_u32_e32 v16, -1, v31
	v_add_u32_e32 v17, 1, v31
	v_fma_f32 v38, -v16, v31, v30
	v_fma_f32 v39, -v17, v31, v30
	v_cmp_ge_f32_e64 s[4:5], 0, v38
	s_waitcnt vmcnt(7)
	v_and_b32_e32 v34, 0xffff0000, v176
	v_lshlrev_b32_e32 v33, 16, v176
	v_mul_f32_e32 v34, v34, v34
	v_cndmask_b32_e64 v16, v31, v16, s[4:5]
	v_cmp_lt_f32_e64 s[4:5], 0, v39
	v_lshlrev_b32_e32 v35, 16, v177
	v_fmac_f32_e32 v34, v33, v33
	v_cndmask_b32_e64 v16, v16, v17, s[4:5]
	v_and_b32_e32 v36, 0xffff0000, v177
	v_fmac_f32_e32 v34, v35, v35
	v_mul_f32_e32 v17, 0x37800000, v16
	v_lshlrev_b32_e32 v37, 16, v178
	v_fmac_f32_e32 v34, v36, v36
	v_cndmask_b32_e32 v16, v16, v17, vcc
	v_cmp_class_f32_e32 vcc, v30, v220
	v_fmac_f32_e32 v34, v37, v37
	s_waitcnt vmcnt(4)
	v_and_b32_e32 v17, 0xffff0000, v191
	v_cndmask_b32_e32 v30, v16, v30, vcc
	v_and_b32_e32 v16, 0xffff0000, v178
	v_fmac_f32_e32 v34, v16, v16
	v_lshlrev_b32_e32 v16, 16, v179
	v_fmac_f32_e32 v34, v16, v16
	v_and_b32_e32 v16, 0xffff0000, v179
	v_fmac_f32_e32 v34, v16, v16
	v_lshlrev_b32_e32 v16, 16, v180
	v_fmac_f32_e32 v34, v16, v16
	v_and_b32_e32 v16, 0xffff0000, v180
	v_fmac_f32_e32 v34, v16, v16
	v_lshlrev_b32_e32 v16, 16, v181
	v_fmac_f32_e32 v34, v16, v16
	v_and_b32_e32 v16, 0xffff0000, v181
	v_fmac_f32_e32 v34, v16, v16
	v_lshlrev_b32_e32 v16, 16, v182
	v_fmac_f32_e32 v34, v16, v16
	v_and_b32_e32 v16, 0xffff0000, v182
	v_fmac_f32_e32 v34, v16, v16
	v_lshlrev_b32_e32 v16, 16, v183
	v_fmac_f32_e32 v34, v16, v16
	v_and_b32_e32 v16, 0xffff0000, v183
	v_fmac_f32_e32 v34, v16, v16
	v_lshlrev_b32_e32 v16, 16, v184
	v_fmac_f32_e32 v34, v16, v16
	v_and_b32_e32 v16, 0xffff0000, v184
	v_fmac_f32_e32 v34, v16, v16
	v_lshlrev_b32_e32 v16, 16, v185
	v_fmac_f32_e32 v34, v16, v16
	v_and_b32_e32 v16, 0xffff0000, v185
	v_fmac_f32_e32 v34, v16, v16
	v_lshlrev_b32_e32 v16, 16, v186
	v_fmac_f32_e32 v34, v16, v16
	v_and_b32_e32 v16, 0xffff0000, v186
	v_fmac_f32_e32 v34, v16, v16
	v_lshlrev_b32_e32 v16, 16, v187
	v_fmac_f32_e32 v34, v16, v16
	v_and_b32_e32 v16, 0xffff0000, v187
	v_fmac_f32_e32 v34, v16, v16
	v_lshlrev_b32_e32 v16, 16, v188
	v_fmac_f32_e32 v34, v16, v16
	v_and_b32_e32 v16, 0xffff0000, v188
	v_fmac_f32_e32 v34, v16, v16
	v_lshlrev_b32_e32 v16, 16, v189
	v_fmac_f32_e32 v34, v16, v16
	v_and_b32_e32 v16, 0xffff0000, v189
	v_fmac_f32_e32 v34, v16, v16
	v_lshlrev_b32_e32 v16, 16, v190
	v_fmac_f32_e32 v34, v16, v16
	v_and_b32_e32 v16, 0xffff0000, v190
	v_fmac_f32_e32 v34, v16, v16
	v_lshlrev_b32_e32 v16, 16, v191
	v_pk_mul_f32 v[16:17], v[16:17], v[16:17]
	s_waitcnt vmcnt(3)
	ds_write_b128 v211, v[4:7]
	s_waitcnt vmcnt(2)
	ds_write_b128 v210, v[8:11] offset:18432
	s_waitcnt vmcnt(1)
	ds_write_b128 v212, v[12:15] offset:18432
	s_waitcnt vmcnt(0)
	ds_write_b128 v211, v[18:21] offset:9216
	v_add_f32_e32 v16, v16, v34
	v_add_f32_e32 v16, v17, v16
	v_mov_b32_e32 v17, v16
	s_nop 1
	v_permlane32_swap_b32_e32 v16, v17
	v_add_f32_e32 v16, v16, v17
	v_mul_f32_e32 v17, 0x4f800000, v16
	v_cmp_gt_f32_e32 vcc, s3, v16
	v_mov_b32_e32 v34, v209
	v_mov_b32_e32 v35, v209
	v_cndmask_b32_e32 v16, v16, v17, vcc
	v_sqrt_f32_e32 v17, v16
	v_mov_b32_e32 v36, v209
	v_mov_b32_e32 v37, v209
	v_mov_b32_e32 v38, v209
	v_add_u32_e32 v31, -1, v17
	v_fma_f32 v33, -v31, v17, v16
	v_cmp_ge_f32_e64 s[4:5], 0, v33
	v_add_u32_e32 v33, 1, v17
	v_mov_b32_e32 v39, v209
	v_cndmask_b32_e64 v31, v17, v31, s[4:5]
	v_fma_f32 v17, -v33, v17, v16
	v_cmp_lt_f32_e64 s[4:5], 0, v17
	v_mov_b32_e32 v55, v209
	v_mov_b32_e32 v56, v209
	v_cndmask_b32_e64 v17, v31, v33, s[4:5]
	v_mul_f32_e32 v31, 0x37800000, v17
	v_cndmask_b32_e32 v17, v17, v31, vcc
	v_cmp_class_f32_e32 vcc, v16, v220
	v_mov_b32_e32 v33, v209
	v_mov_b32_e32 v57, v209
	v_cndmask_b32_e32 v16, v17, v16, vcc
	v_add_co_u32_e32 v4, vcc, s0, v22
	v_mul_f32_e32 v16, v30, v16
	s_nop 0
	v_addc_co_u32_e32 v5, vcc, 0, v23, vcc
	global_load_dwordx4 v[192:195], v[4:5], off
	global_load_dwordx4 v[196:199], v[24:25], off offset:128
	global_load_dwordx4 v[200:203], v[26:27], off offset:128
	v_and_b32_e32 v4, 4, v28
	v_or3_b32 v0, v1, v0, v4
	v_mad_u32_u24 v213, v0, s20, v208
	s_waitcnt lgkmcnt(0)
	s_barrier
	ds_read_b128 v[4:7], v213
	ds_read_b128 v[8:11], v213 offset:32
	v_fmamk_f32 v16, v16, 0x3f8147ae, v221
	v_xor_b32_e32 v16, 0x80000000, v16
	v_mov_b32_e32 v17, v16
	v_mov_b32_e32 v18, v16
	v_mov_b32_e32 v19, v16
	v_mov_b32_e32 v20, v16
	v_mov_b32_e32 v21, v16
	v_mov_b32_e32 v22, v16
	v_mov_b32_e32 v23, v16
	v_mov_b32_e32 v24, v16
	v_mov_b32_e32 v25, v16
	v_mov_b32_e32 v26, v16
	v_mov_b32_e32 v27, v16
	v_mov_b32_e32 v28, v16
	v_mov_b32_e32 v29, v16
	v_mov_b32_e32 v30, v16
	v_mov_b32_e32 v31, v16
	v_mad_u32_u24 v208, v32, s20, v208
	v_mov_b32_e32 v0, 0
	s_waitcnt lgkmcnt(1)
	v_mfma_f32_32x32x16_bf16 v[96:111], v[4:7], v[176:179], v[16:31]
	ds_read_b128 v[4:7], v213 offset:4608
	ds_read_b128 v[12:15], v213 offset:4640
	v_mov_b32_e32 v1, v209
	v_mov_b32_e32 v32, 0
	v_mov_b32_e32 v58, v209
	v_mov_b32_e32 v59, v209
	v_mov_b32_e32 v60, v209
	v_mov_b32_e32 v61, v209
	s_waitcnt lgkmcnt(2)
	v_mfma_f32_32x32x16_bf16 v[96:111], v[8:11], v[180:183], v[96:111]
	v_mov_b32_e32 v62, v209
	v_mov_b32_e32 v63, v209
	v_mov_b32_e32 v64, 0
	v_mov_b32_e32 v65, v209
	v_mov_b32_e32 v66, v209
	v_mov_b32_e32 v67, v209
	v_mov_b32_e32 v68, v209
	s_waitcnt lgkmcnt(1)
	v_mfma_f32_32x32x16_bf16 v[80:95], v[4:7], v[176:179], v[16:31]
	ds_read_b128 v[4:7], v213 offset:64
	ds_read_b128 v[8:11], v213 offset:96
	v_mov_b32_e32 v69, v209
	v_mov_b32_e32 v70, v209
	v_mov_b32_e32 v71, v209
	v_mov_b32_e32 v72, v209
	v_mov_b32_e32 v73, v209
	v_mov_b32_e32 v74, v209
	s_waitcnt lgkmcnt(1)
	v_mfma_f32_32x32x16_bf16 v[96:111], v[4:7], v[184:187], v[96:111]
	v_mov_b32_e32 v75, v209
	v_mov_b32_e32 v76, v209
	v_mov_b32_e32 v77, v209
	v_mov_b32_e32 v78, v209
	v_mov_b32_e32 v79, v209
	v_mfma_f32_32x32x16_bf16 v[80:95], v[12:15], v[180:183], v[80:95]
	v_mov_b32_e32 v12, v209
	v_mov_b32_e32 v13, v209
	v_mov_b32_e32 v14, v209
	v_mov_b32_e32 v15, v209
	s_waitcnt lgkmcnt(0)
	v_mfma_f32_32x32x16_bf16 v[96:111], v[8:11], v[188:191], v[96:111]
	ds_read_b128 v[4:7], v213 offset:4672
	ds_read_b128 v[8:11], v213 offset:4704
	s_waitcnt lgkmcnt(1)
	v_mfma_f32_32x32x16_bf16 v[80:95], v[4:7], v[184:187], v[80:95]
	v_mov_b32_e32 v4, v209
	v_mov_b32_e32 v5, v209
	v_mov_b32_e32 v6, v209
	v_mov_b32_e32 v7, v209
	s_waitcnt lgkmcnt(0)
	v_mfma_f32_32x32x16_bf16 v[80:95], v[8:11], v[188:191], v[80:95]
	v_mov_b32_e32 v8, v209
	v_mov_b32_e32 v9, v209
	v_mov_b32_e32 v10, v209
	v_mov_b32_e32 v11, v209
	s_branch .LBB0_578
	s_nop 0
	s_nop 0
	s_nop 0
	s_nop 0
	s_nop 0
	s_nop 0
	s_nop 0
	s_nop 0
	s_nop 0
	s_nop 0
	s_nop 0
	s_nop 0
	s_nop 0
	s_nop 0

; template <int DQK, int DV>
; __device__ __forceinline__ void attn_pass(const bf16_t* __restrict__ qh, const bf16_t* __restrict__ kh, const bf16_t* __restrict__ vth, int q0, char* smem, f32x16 (&o)[DV / 32], float kmax, int wvp) {
;     ...
; #pragma unroll
;   for (int ks = 0; ks < NKS; ++ks) asm volatile("" :: "v"(qf[ks]));
; #pragma unroll 1
;   for (int kt = 0; kt < NT; kt += 2) {
;     STEP(sA, sB, kt);
;     STEP(sB, sA, kt + 1);
;   }
.LBB0_593:
	v_mov_b64_e32 v[80:81], v[160:161]
	v_mov_b64_e32 v[96:97], v[128:129]
	v_mov_b64_e32 v[82:83], v[162:163]
	v_mov_b64_e32 v[84:85], v[164:165]
	v_mov_b64_e32 v[86:87], v[166:167]
	v_mov_b64_e32 v[88:89], v[168:169]
	v_mov_b64_e32 v[90:91], v[170:171]
	v_mov_b64_e32 v[92:93], v[172:173]
	v_mov_b64_e32 v[94:95], v[174:175]
	v_mov_b64_e32 v[98:99], v[130:131]
	v_mov_b64_e32 v[100:101], v[132:133]
	v_mov_b64_e32 v[102:103], v[134:135]
	v_mov_b64_e32 v[104:105], v[136:137]
	v_mov_b64_e32 v[106:107], v[138:139]
	v_mov_b64_e32 v[108:109], v[140:141]
	v_mov_b64_e32 v[110:111], v[142:143]
	s_branch .LBB0_577
	s_nop 0
	s_nop 0
